# xn_phase (both sites) rewritten: all loads of a row issued up front, ln gamma/beta hoisted, each wave takes 17 contiguous rows
# speedup vs baseline: 1.0033x; 1.0029x over previous
; DI int ltid() { int t = threadIdx.x; asm volatile("" : "+v"(t)); return t; }
; DI void xn_phase(const Params& p, const float* stats, const float* g, const float* bta, int l, int sc_off, int sh_off) {
;   const int tid = ltid(), wave = tid >> 6, lane = tid & 63;
;   for (int row = blockIdx.x * 4 + wave; row < NTOK; row += gridDim.x * 4) {
;     const int b = row / TPB, s = row % TPB;
;     const int mi = s < CTXL ? 8 : b;
;     const float* mv = p.modv + ((size_t)l * 9 + mi) * 6144;
;     const f32x4* xr = (const f32x4*)(stats ? p.X + (size_t)row * 1024 : in_row(p, row));
;     const f32x4 xv0 = xr[lane], xv1 = xr[lane + 64], xv2 = xr[lane + 128], xv3 = xr[lane + 192];
;     float mean = 0.f, rstd = 1.f;
;     if (stats) row_stats(stats, row, mean, rstd);
;     uint2* dst = (uint2*)(p.XN + (size_t)row * 1024);
.LBB0_51:
	s_mov_b64 s[4:5], 0
	v_writelane_b32 v255, s4, 49
	s_nop 1
	v_writelane_b32 v255, s5, 50
	s_cbranch_execz .LBB0_70
	v_mov_b32_e32 v0, v216
	v_readlane_b32 s0, v253, 54
	v_ashrrev_i32_e32 v1, 6, v0
	s_nop 0
	v_add_u32_e32 v16, s0, v1
	s_mov_b32 s0, 0x8800
	v_cmp_gt_i32_e32 vcc, s0, v16
	s_and_saveexec_b64 s[0:1], vcc
	s_cbranch_execz .LBB0_69
	v_readlane_b32 s4, v255, 44
	v_readlane_b32 s8, v253, 57
	v_readlane_b32 s5, v255, 45
	s_mov_b32 s24, s4
	s_lshl_b32 s4, s4, 10
	v_readlane_b32 s9, v253, 58
	s_ashr_i32 s5, s4, 31
	v_readlane_b32 s8, v254, 11
	s_lshl_b64 s[4:5], s[4:5], 2
	v_readlane_b32 s14, v253, 63
	v_readlane_b32 s9, v254, 12
	v_readlane_b32 s15, v254, 0
	s_add_u32 s6, s14, s4
	s_load_dword s2, s[8:9], 0x0
	v_readlane_b32 s8, v255, 46
	v_readlane_b32 s12, v253, 61
	s_addc_u32 s7, s15, s5
	v_readlane_b32 s9, v255, 47
	v_readlane_b32 s13, v253, 62
	s_add_u32 s4, s12, s4
	v_and_b32_e32 v18, 63, v0
	s_mul_hi_i32 s9, s24, 9
	v_readlane_b32 s10, v253, 59
	v_readlane_b32 s11, v253, 60
	v_readlane_b32 s16, v254, 1
	v_readlane_b32 s17, v254, 2
	v_readlane_b32 s18, v254, 3
	v_readlane_b32 s19, v254, 4
	s_addc_u32 s5, s13, s5
	v_writelane_b32 v255, s8, 46
	v_lshlrev_b32_e32 v0, 4, v18
	v_mov_b32_e32 v1, v144
	v_writelane_b32 v255, s9, 47
	v_lshl_add_u64 v[20:21], s[4:5], 0, v[0:1]
	v_lshl_add_u64 v[22:23], s[6:7], 0, v[0:1]
	v_readlane_b32 s4, v254, 59
	v_or_b32_e32 v0, 64, v18
	v_or_b32_e32 v2, 0x80, v18
	v_or_b32_e32 v4, 0xc0, v18
	v_lshlrev_b32_e32 v6, 3, v18
	v_mov_b32_e32 v7, v144
	v_readlane_b32 s10, v255, 1
	v_readlane_b32 s11, v255, 2
	v_readlane_b32 s16, v255, 7
	v_readlane_b32 s17, v255, 8
	s_waitcnt lgkmcnt(0)
	s_lshl_b32 s2, s2, 2
	s_mov_b64 s[10:11], 0
	v_lshl_add_u64 v[24:25], s[16:17], 0, v[6:7]
	v_lshlrev_b32_e32 v26, 4, v0
	v_lshlrev_b32_e32 v28, 4, v2
	v_lshlrev_b32_e32 v30, 4, v4
	v_readlane_b32 s20, v254, 5
	v_readlane_b32 s21, v254, 6
	v_readlane_b32 s22, v254, 7
	v_readlane_b32 s23, v254, 8
	v_readlane_b32 s5, v254, 60
	v_readlane_b32 s6, v254, 61
	v_readlane_b32 s7, v254, 62
	v_readlane_b32 s8, v254, 63
	v_readlane_b32 s9, v255, 0
	v_readlane_b32 s12, v255, 3
	v_readlane_b32 s13, v255, 4
	v_readlane_b32 s14, v255, 5
	v_readlane_b32 s15, v255, 6
	v_readlane_b32 s18, v255, 9
	v_readlane_b32 s19, v255, 10
	s_and_b64 vcc, exec, s[28:29]
	s_cbranch_vccnz .LxnF1_pre
	s_branch .LBB0_55
.LxnF1_pre:
	v_readlane_b32 s12, v254, 59
	v_readlane_b32 s13, v254, 60
	global_load_dwordx4 v[88:91], v[20:21], off
	global_load_dwordx4 v[92:95], v[20:21], off offset:1024
	global_load_dwordx4 v[96:99], v[20:21], off offset:2048
	global_load_dwordx4 v[100:103], v[20:21], off offset:3072
	global_load_dwordx4 v[104:107], v[22:23], off
	global_load_dwordx4 v[108:111], v[22:23], off offset:1024
	global_load_dwordx4 v[112:115], v[22:23], off offset:2048
	global_load_dwordx4 v[116:119], v[22:23], off offset:3072
	v_mul_u32_u24_e32 v16, 17, v16
	s_mov_b32 s6, 17
	v_lshlrev_b32_e32 v38, 4, v18
	v_mov_b32_e32 v39, v144
; DI int ltid() { int t = threadIdx.x; asm volatile("" : "+v"(t)); return t; }
; DI unsigned pack2(float a, float b) { f2 v = {a, b}; bf2 c = __builtin_convertvector(v, bf2); return __builtin_bit_cast(unsigned, c); }
; DI void xn_phase(const Params& p, const float* stats, const float* g, const float* bta, int l, int sc_off, int sh_off) {
;   const int tid = ltid(), wave = tid >> 6, lane = tid & 63;
;   for (int row = blockIdx.x * 4 + wave; row < NTOK; row += gridDim.x * 4) {
;     const int b = row / TPB, s = row % TPB;
;     const int mi = s < CTXL ? 8 : b;
;     const float* mv = p.modv + ((size_t)l * 9 + mi) * 6144;
;     const f32x4* xr = (const f32x4*)(stats ? p.X + (size_t)row * 1024 : in_row(p, row));
;     const f32x4 xv0 = xr[lane], xv1 = xr[lane + 64], xv2 = xr[lane + 128], xv3 = xr[lane + 192];
;     float mean = 0.f, rstd = 1.f;
;     if (stats) row_stats(stats, row, mean, rstd);
;     uint2* dst = (uint2*)(p.XN + (size_t)row * 1024);
; #pragma unroll
;     for (int j = 0; j < 4; ++j) {
;       const int c4 = lane + 64 * j;
;       const f32x4 vq = j == 0 ? xv0 : (j == 1 ? xv1 : (j == 2 ? xv2 : xv3));
;       float4 v = make_float4(vq.x, vq.y, vq.z, vq.w);
;       if (stats) {
;         float4 gv = ((const float4*)g)[c4], bv = ((const float4*)bta)[c4];
;         v.x = (v.x - mean) * rstd * gv.x + bv.x; v.y = (v.y - mean) * rstd * gv.y + bv.y;
;         v.z = (v.z - mean) * rstd * gv.z + bv.z; v.w = (v.w - mean) * rstd * gv.w + bv.w;
;       }
;       float4 sc = ((const float4*)(mv + sc_off))[c4], sh = ((const float4*)(mv + sh_off))[c4];
;       uint2 o;
;       o.x = pack2(v.x * (1.f + sc.x) + sh.x, v.y * (1.f + sc.y) + sh.y);
;       o.y = pack2(v.z * (1.f + sc.z) + sh.z, v.w * (1.f + sc.w) + sh.w);
;       dst[c4] = o;
;     }
;   }
.LxnF1_loop:
	s_mov_b32 s4, 0x78787879
	v_mul_hi_i32 v0, v16, s4
	v_lshrrev_b32_e32 v1, 31, v0
	v_ashrrev_i32_e32 v0, 11, v0
	v_add_u32_e32 v34, v0, v1
	v_mul_i32_i24_e32 v0, 0x1100, v34
	v_sub_u32_e32 v4, v16, v0
	v_cmp_gt_i32_e64 s[8:9], s33, v4
	v_ashrrev_i32_e32 v17, 31, v16
	v_mov_b64_e32 v[2:3], s[58:59]
	v_mov_b64_e32 v[0:1], v[16:17]
	v_lshlrev_b64 v[0:1], 12, v[0:1]
	v_lshl_add_u64 v[0:1], v[2:3], 0, v[0:1]
	v_lshl_add_u64 v[0:1], v[0:1], 0, v[38:39]
	v_lshlrev_b64 v[32:33], 6, v[16:17]
	v_lshl_add_u64 v[32:33], s[12:13], 0, v[32:33]
	global_load_dwordx4 v[56:59], v[32:33], off
	global_load_dwordx4 v[60:63], v[32:33], off offset:16
	global_load_dwordx4 v[64:67], v[32:33], off offset:32
	global_load_dwordx4 v[68:71], v[32:33], off offset:48
	global_load_dwordx4 v[72:75], v[0:1], off
	global_load_dwordx4 v[76:79], v[0:1], off offset:1024
	global_load_dwordx4 v[80:83], v[0:1], off offset:2048
	global_load_dwordx4 v[84:87], v[0:1], off offset:3072
	v_cndmask_b32_e64 v34, v34, 8, s[8:9]
	v_readlane_b32 s4, v255, 46
	v_ashrrev_i32_e32 v35, 31, v34
	v_readlane_b32 s5, v255, 47
	v_mov_b64_e32 v[36:37], s[68:69]
	s_movk_i32 s8, 0x6000
	v_lshl_add_u64 v[34:35], s[4:5], 0, v[34:35]
	v_mad_u64_u32 v[44:45], s[4:5], v34, s8, v[36:37]
	v_mov_b32_e32 v34, v45
	v_mad_u64_u32 v[34:35], s[4:5], v35, s8, v[34:35]
	v_mov_b32_e32 v45, v34
	s_mov_b64 s[4:5], 0x4000
	v_lshl_add_u64 v[36:37], v[44:45], 0, s[4:5]
	s_mov_b64 s[4:5], 0x3000
	v_lshl_add_u64 v[44:45], v[44:45], 0, s[4:5]
	v_lshl_add_u64 v[40:41], v[36:37], 0, v[38:39]
	v_lshl_add_u64 v[42:43], v[44:45], 0, v[38:39]
	global_load_dwordx4 v[120:123], v[40:41], off
	global_load_dwordx4 v[124:127], v[40:41], off offset:1024
	global_load_dwordx4 v[128:131], v[40:41], off offset:2048
	global_load_dwordx4 v[132:135], v[40:41], off offset:3072
	global_load_dwordx4 v[146:149], v[42:43], off
	global_load_dwordx4 v[150:153], v[42:43], off offset:1024
	global_load_dwordx4 v[154:157], v[42:43], off offset:2048
	global_load_dwordx4 v[158:161], v[42:43], off offset:3072
	v_lshlrev_b64 v[34:35], 11, v[16:17]
	v_lshl_add_u64 v[34:35], v[24:25], 0, v[34:35]
	s_waitcnt vmcnt(12)
	v_add_f32_e32 v2, v56, v58
	v_add_f32_e32 v3, v57, v59
	v_add_f32_e32 v4, v60, v62
	v_add_f32_e32 v5, v61, v63
	v_add_f32_e32 v2, v2, v4
	v_add_f32_e32 v3, v3, v5
	v_add_f32_e32 v4, v64, v66
	v_add_f32_e32 v5, v65, v67
	v_add_f32_e32 v2, v2, v4
	v_add_f32_e32 v3, v3, v5
	v_add_f32_e32 v4, v68, v70
	v_add_f32_e32 v5, v69, v71
	v_add_f32_e32 v2, v2, v4
	v_add_f32_e32 v3, v3, v5
	v_mul_f32_e32 v36, 0x3a800000, v2
	v_mul_f32_e32 v3, 0x3a800000, v3
	v_fma_f32 v19, -v36, v36, v3
	v_max_f32_e32 v19, 0, v19
	v_add_f32_e32 v19, 0x3727c5ac, v19
	v_mul_f32_e32 v27, 0x4b800000, v19
	s_mov_b32 s4, 0x800000
	v_cmp_gt_f32_e32 vcc, s4, v19
	s_nop 1
	v_cndmask_b32_e32 v19, v19, v27, vcc
	v_rsq_f32_e32 v19, v19
	s_nop 0
	v_mul_f32_e32 v27, 0x45800000, v19
	v_cndmask_b32_e32 v32, v19, v27, vcc
	s_waitcnt vmcnt(0)
	v_pk_add_f32 v[72:73], v[72:73], v[36:37] op_sel_hi:[1,0] neg_lo:[0,1] neg_hi:[0,1]
	v_pk_add_f32 v[74:75], v[74:75], v[36:37] op_sel_hi:[1,0] neg_lo:[0,1] neg_hi:[0,1]
	v_pk_add_f32 v[76:77], v[76:77], v[36:37] op_sel_hi:[1,0] neg_lo:[0,1] neg_hi:[0,1]
	v_pk_add_f32 v[78:79], v[78:79], v[36:37] op_sel_hi:[1,0] neg_lo:[0,1] neg_hi:[0,1]
	v_pk_add_f32 v[80:81], v[80:81], v[36:37] op_sel_hi:[1,0] neg_lo:[0,1] neg_hi:[0,1]
	v_pk_add_f32 v[82:83], v[82:83], v[36:37] op_sel_hi:[1,0] neg_lo:[0,1] neg_hi:[0,1]
	v_pk_add_f32 v[84:85], v[84:85], v[36:37] op_sel_hi:[1,0] neg_lo:[0,1] neg_hi:[0,1]
	v_pk_add_f32 v[86:87], v[86:87], v[36:37] op_sel_hi:[1,0] neg_lo:[0,1] neg_hi:[0,1]
	v_pk_add_f32 v[120:121], v[120:121], 1.0 op_sel_hi:[1,0]
	v_pk_add_f32 v[122:123], v[122:123], 1.0 op_sel_hi:[1,0]
	v_pk_add_f32 v[124:125], v[124:125], 1.0 op_sel_hi:[1,0]
	v_pk_add_f32 v[126:127], v[126:127], 1.0 op_sel_hi:[1,0]
	v_pk_add_f32 v[128:129], v[128:129], 1.0 op_sel_hi:[1,0]
	v_pk_add_f32 v[130:131], v[130:131], 1.0 op_sel_hi:[1,0]
	v_pk_add_f32 v[132:133], v[132:133], 1.0 op_sel_hi:[1,0]
	v_pk_add_f32 v[134:135], v[134:135], 1.0 op_sel_hi:[1,0]
	v_pk_mul_f32 v[72:73], v[32:33], v[72:73] op_sel_hi:[0,1]
	v_pk_mul_f32 v[74:75], v[32:33], v[74:75] op_sel_hi:[0,1]
	v_pk_mul_f32 v[76:77], v[32:33], v[76:77] op_sel_hi:[0,1]
	v_pk_mul_f32 v[78:79], v[32:33], v[78:79] op_sel_hi:[0,1]
	v_pk_mul_f32 v[80:81], v[32:33], v[80:81] op_sel_hi:[0,1]
	v_pk_mul_f32 v[82:83], v[32:33], v[82:83] op_sel_hi:[0,1]
	v_pk_mul_f32 v[84:85], v[32:33], v[84:85] op_sel_hi:[0,1]
	v_pk_mul_f32 v[86:87], v[32:33], v[86:87] op_sel_hi:[0,1]
	v_pk_fma_f32 v[72:73], v[72:73], v[88:89], v[104:105]
	v_pk_fma_f32 v[74:75], v[74:75], v[90:91], v[106:107]
	v_pk_fma_f32 v[76:77], v[76:77], v[92:93], v[108:109]
	v_pk_fma_f32 v[78:79], v[78:79], v[94:95], v[110:111]
	v_pk_fma_f32 v[80:81], v[80:81], v[96:97], v[112:113]
	v_pk_fma_f32 v[82:83], v[82:83], v[98:99], v[114:115]
	v_pk_fma_f32 v[84:85], v[84:85], v[100:101], v[116:117]
	v_pk_fma_f32 v[86:87], v[86:87], v[102:103], v[118:119]
	v_pk_fma_f32 v[72:73], v[72:73], v[120:121], v[146:147]
	v_pk_fma_f32 v[74:75], v[74:75], v[122:123], v[148:149]
	v_pk_fma_f32 v[76:77], v[76:77], v[124:125], v[150:151]
	v_pk_fma_f32 v[78:79], v[78:79], v[126:127], v[152:153]
	v_pk_fma_f32 v[80:81], v[80:81], v[128:129], v[154:155]
	v_pk_fma_f32 v[82:83], v[82:83], v[130:131], v[156:157]
	v_pk_fma_f32 v[84:85], v[84:85], v[132:133], v[158:159]
	v_pk_fma_f32 v[86:87], v[86:87], v[134:135], v[160:161]
	v_cvt_pk_bf16_f32 v72, v72, v73
	v_cvt_pk_bf16_f32 v73, v74, v75
	v_cvt_pk_bf16_f32 v76, v76, v77
	v_cvt_pk_bf16_f32 v77, v78, v79
	v_cvt_pk_bf16_f32 v80, v80, v81
	v_cvt_pk_bf16_f32 v81, v82, v83
	v_cvt_pk_bf16_f32 v84, v84, v85
	v_cvt_pk_bf16_f32 v85, v86, v87
	global_store_dwordx2 v[34:35], v[72:73], off
	global_store_dwordx2 v[34:35], v[76:77], off offset:512
	global_store_dwordx2 v[34:35], v[80:81], off offset:1024
	global_store_dwordx2 v[34:35], v[84:85], off offset:1536
	v_add_u32_e32 v16, 1, v16
	s_sub_i32 s6, s6, 1
	s_cmp_lg_u32 s6, 0
	s_cbranch_scc1 .LxnF1_loop
	s_branch .LBB0_69

; DI int ltid() { int t = threadIdx.x; asm volatile("" : "+v"(t)); return t; }
; DI void xn_phase(const Params& p, const float* stats, const float* g, const float* bta, int l, int sc_off, int sh_off) {
;   const int tid = ltid(), wave = tid >> 6, lane = tid & 63;
;   for (int row = blockIdx.x * 4 + wave; row < NTOK; row += gridDim.x * 4) {
;     const int b = row / TPB, s = row % TPB;
;     const int mi = s < CTXL ? 8 : b;
;     const float* mv = p.modv + ((size_t)l * 9 + mi) * 6144;
;     const f32x4* xr = (const f32x4*)(stats ? p.X + (size_t)row * 1024 : in_row(p, row));
;     const f32x4 xv0 = xr[lane], xv1 = xr[lane + 64], xv2 = xr[lane + 128], xv3 = xr[lane + 192];
;     float mean = 0.f, rstd = 1.f;
;     if (stats) row_stats(stats, row, mean, rstd);
;     uint2* dst = (uint2*)(p.XN + (size_t)row * 1024);
.LBB0_960:
	s_and_b64 vcc, exec, s[4:5]
	s_cbranch_vccz .LBB0_1011
	v_mov_b32_e32 v0, v216
	v_readlane_b32 s0, v253, 54
	v_ashrrev_i32_e32 v1, 6, v0
	s_nop 0
	v_add_u32_e32 v16, s0, v1
	s_mov_b32 s0, 0x8800
	v_cmp_gt_i32_e32 vcc, s0, v16
	s_and_saveexec_b64 s[0:1], vcc
	v_readlane_b32 s10, v253, 2
	s_mov_b64 s[28:29], 0x1000
	s_mov_b32 s30, 0x87ff
	v_readlane_b32 s11, v253, 3
	s_cbranch_execz .LBB0_978
	v_readlane_b32 s4, v255, 44
	s_lshl_b32 s2, s4, 10
	v_readlane_b32 s5, v255, 45
	s_addk_i32 s2, 0xfc00
	v_readlane_b32 s12, v253, 57
	s_mov_b32 s34, s4
	s_lshl_b64 s[4:5], s[2:3], 2
	v_readlane_b32 s22, v254, 3
	v_readlane_b32 s23, v254, 4
	s_add_u32 s2, s22, s4
	v_readlane_b32 s20, v254, 1
	s_addc_u32 s6, s23, s5
	v_readlane_b32 s21, v254, 2
	s_add_u32 s8, s20, s4
	s_addc_u32 s7, s21, s5
	s_cmp_gt_i32 s10, 10
	s_cselect_b32 s5, s6, 0
	s_cselect_b32 s6, s8, 0
	v_readlane_b32 s8, v254, 11
	v_readlane_b32 s9, v254, 12
	v_readlane_b32 s13, v253, 58
	v_readlane_b32 s14, v253, 59
	v_readlane_b32 s15, v253, 60
	v_readlane_b32 s16, v253, 61
	v_readlane_b32 s17, v253, 62
	v_readlane_b32 s18, v253, 63
	v_readlane_b32 s19, v254, 0
	v_readlane_b32 s24, v254, 5
	v_readlane_b32 s25, v254, 6
	v_readlane_b32 s26, v254, 7
	v_readlane_b32 s27, v254, 8
	s_cselect_b32 s4, s2, 0
	s_load_dword s2, s[8:9], 0x0
	v_readlane_b32 s12, v254, 59
	v_readlane_b32 s8, v255, 46
	v_readlane_b32 s14, v254, 61
	v_readlane_b32 s15, v254, 62
	v_and_b32_e32 v18, 63, v0
	v_readlane_b32 s9, v255, 47
	s_cselect_b32 s11, s15, 0
	s_cselect_b32 s10, s14, 0
	s_cselect_b32 s7, s7, 0
	s_mul_hi_i32 s9, s34, 9
	v_lshlrev_b32_e32 v0, 4, v18
	v_mov_b32_e32 v1, v144
	v_readlane_b32 s13, v254, 60
	v_readlane_b32 s17, v255, 0
	v_readlane_b32 s18, v255, 1
	v_readlane_b32 s19, v255, 2
	v_readlane_b32 s20, v255, 3
	v_readlane_b32 s21, v255, 4
	v_readlane_b32 s22, v255, 5
	v_readlane_b32 s23, v255, 6
	v_readlane_b32 s24, v255, 7
	v_readlane_b32 s25, v255, 8
	v_readlane_b32 s26, v255, 9
	v_readlane_b32 s27, v255, 10
	v_writelane_b32 v255, s8, 46
	s_cmp_lg_u64 s[10:11], 0
	v_lshl_add_u64 v[20:21], s[6:7], 0, v[0:1]
	v_lshl_add_u64 v[22:23], s[4:5], 0, v[0:1]
	v_or_b32_e32 v0, 64, v18
	v_or_b32_e32 v2, 0x80, v18
	v_or_b32_e32 v4, 0xc0, v18
	v_lshlrev_b32_e32 v6, 3, v18
	v_mov_b32_e32 v7, v144
	v_writelane_b32 v255, s9, 47
	s_mov_b64 s[12:13], 0
	s_cselect_b64 s[14:15], -1, 0
	s_waitcnt lgkmcnt(0)
	s_lshl_b32 s2, s2, 2
	v_lshl_add_u64 v[24:25], s[24:25], 0, v[6:7]
	v_lshlrev_b32_e32 v26, 4, v0
	v_lshlrev_b32_e32 v28, 4, v2
	v_lshlrev_b32_e32 v30, 4, v4
	v_readlane_b32 s16, v254, 63
	s_and_b64 vcc, exec, s[14:15]
	s_cbranch_vccnz .LxnF2_pre
	s_branch .LBB0_964
.LxnF2_pre:
	global_load_dwordx4 v[88:91], v[20:21], off
	global_load_dwordx4 v[92:95], v[20:21], off offset:1024
	global_load_dwordx4 v[96:99], v[20:21], off offset:2048
	global_load_dwordx4 v[100:103], v[20:21], off offset:3072
	global_load_dwordx4 v[104:107], v[22:23], off
	global_load_dwordx4 v[108:111], v[22:23], off offset:1024
	global_load_dwordx4 v[112:115], v[22:23], off offset:2048
	global_load_dwordx4 v[116:119], v[22:23], off offset:3072
	v_mul_u32_u24_e32 v16, 17, v16
	s_mov_b32 s6, 17
	v_lshlrev_b32_e32 v38, 4, v18
	v_mov_b32_e32 v39, v144
; DI int ltid() { int t = threadIdx.x; asm volatile("" : "+v"(t)); return t; }
; DI unsigned pack2(float a, float b) { f2 v = {a, b}; bf2 c = __builtin_convertvector(v, bf2); return __builtin_bit_cast(unsigned, c); }
; DI void xn_phase(const Params& p, const float* stats, const float* g, const float* bta, int l, int sc_off, int sh_off) {
;   const int tid = ltid(), wave = tid >> 6, lane = tid & 63;
;   for (int row = blockIdx.x * 4 + wave; row < NTOK; row += gridDim.x * 4) {
;     const int b = row / TPB, s = row % TPB;
;     const int mi = s < CTXL ? 8 : b;
;     const float* mv = p.modv + ((size_t)l * 9 + mi) * 6144;
;     const f32x4* xr = (const f32x4*)(stats ? p.X + (size_t)row * 1024 : in_row(p, row));
;     const f32x4 xv0 = xr[lane], xv1 = xr[lane + 64], xv2 = xr[lane + 128], xv3 = xr[lane + 192];
;     float mean = 0.f, rstd = 1.f;
;     if (stats) row_stats(stats, row, mean, rstd);
;     uint2* dst = (uint2*)(p.XN + (size_t)row * 1024);
; #pragma unroll
;     for (int j = 0; j < 4; ++j) {
;       const int c4 = lane + 64 * j;
;       const f32x4 vq = j == 0 ? xv0 : (j == 1 ? xv1 : (j == 2 ? xv2 : xv3));
;       float4 v = make_float4(vq.x, vq.y, vq.z, vq.w);
;       if (stats) {
;         float4 gv = ((const float4*)g)[c4], bv = ((const float4*)bta)[c4];
;         v.x = (v.x - mean) * rstd * gv.x + bv.x; v.y = (v.y - mean) * rstd * gv.y + bv.y;
;         v.z = (v.z - mean) * rstd * gv.z + bv.z; v.w = (v.w - mean) * rstd * gv.w + bv.w;
;       }
;       float4 sc = ((const float4*)(mv + sc_off))[c4], sh = ((const float4*)(mv + sh_off))[c4];
;       uint2 o;
;       o.x = pack2(v.x * (1.f + sc.x) + sh.x, v.y * (1.f + sc.y) + sh.y);
;       o.y = pack2(v.z * (1.f + sc.z) + sh.z, v.w * (1.f + sc.w) + sh.w);
;       dst[c4] = o;
;     }
;   }
.LxnF2_loop:
	s_mov_b32 s4, 0x78787879
	v_mul_hi_i32 v0, v16, s4
	v_lshrrev_b32_e32 v1, 31, v0
	v_ashrrev_i32_e32 v0, 11, v0
	v_add_u32_e32 v34, v0, v1
	v_mul_i32_i24_e32 v0, 0x1100, v34
	v_sub_u32_e32 v4, v16, v0
	v_cmp_gt_i32_e64 s[8:9], s33, v4
	v_ashrrev_i32_e32 v17, 31, v16
	v_mov_b64_e32 v[2:3], s[58:59]
	v_mov_b64_e32 v[0:1], v[16:17]
	v_lshlrev_b64 v[0:1], 12, v[0:1]
	v_lshl_add_u64 v[0:1], v[2:3], 0, v[0:1]
	v_lshl_add_u64 v[0:1], v[0:1], 0, v[38:39]
	v_lshlrev_b64 v[32:33], 6, v[16:17]
	v_lshl_add_u64 v[32:33], s[10:11], 0, v[32:33]
	global_load_dwordx4 v[56:59], v[32:33], off
	global_load_dwordx4 v[60:63], v[32:33], off offset:16
	global_load_dwordx4 v[64:67], v[32:33], off offset:32
	global_load_dwordx4 v[68:71], v[32:33], off offset:48
	global_load_dwordx4 v[72:75], v[0:1], off
	global_load_dwordx4 v[76:79], v[0:1], off offset:1024
	global_load_dwordx4 v[80:83], v[0:1], off offset:2048
	global_load_dwordx4 v[84:87], v[0:1], off offset:3072
	v_cndmask_b32_e64 v34, v34, 8, s[8:9]
	v_readlane_b32 s4, v255, 46
	v_ashrrev_i32_e32 v35, 31, v34
	v_readlane_b32 s5, v255, 47
	v_mov_b64_e32 v[36:37], s[68:69]
	s_movk_i32 s8, 0x6000
	v_lshl_add_u64 v[34:35], s[4:5], 0, v[34:35]
	v_mad_u64_u32 v[44:45], s[4:5], v34, s8, v[36:37]
	v_mov_b32_e32 v34, v45
	v_mad_u64_u32 v[34:35], s[4:5], v35, s8, v[34:35]
	v_mov_b32_e32 v45, v34
	v_lshl_add_u64 v[36:37], v[44:45], 0, s[28:29]
	v_lshl_add_u64 v[40:41], v[36:37], 0, v[38:39]
	v_lshl_add_u64 v[42:43], v[44:45], 0, v[38:39]
	global_load_dwordx4 v[120:123], v[40:41], off
	global_load_dwordx4 v[124:127], v[40:41], off offset:1024
	global_load_dwordx4 v[128:131], v[40:41], off offset:2048
	global_load_dwordx4 v[132:135], v[40:41], off offset:3072
	global_load_dwordx4 v[146:149], v[42:43], off
	global_load_dwordx4 v[150:153], v[42:43], off offset:1024
	global_load_dwordx4 v[154:157], v[42:43], off offset:2048
	global_load_dwordx4 v[158:161], v[42:43], off offset:3072
	v_lshlrev_b64 v[34:35], 11, v[16:17]
	v_lshl_add_u64 v[34:35], v[24:25], 0, v[34:35]
	s_waitcnt vmcnt(12)
	v_add_f32_e32 v2, v56, v58
	v_add_f32_e32 v3, v57, v59
	v_add_f32_e32 v4, v60, v62
	v_add_f32_e32 v5, v61, v63
	v_add_f32_e32 v2, v2, v4
	v_add_f32_e32 v3, v3, v5
	v_add_f32_e32 v4, v64, v66
	v_add_f32_e32 v5, v65, v67
	v_add_f32_e32 v2, v2, v4
	v_add_f32_e32 v3, v3, v5
	v_add_f32_e32 v4, v68, v70
	v_add_f32_e32 v5, v69, v71
	v_add_f32_e32 v2, v2, v4
	v_add_f32_e32 v3, v3, v5
	v_mul_f32_e32 v36, 0x3a800000, v2
	v_mul_f32_e32 v3, 0x3a800000, v3
	v_fma_f32 v19, -v36, v36, v3
	v_max_f32_e32 v19, 0, v19
	v_add_f32_e32 v19, 0x3727c5ac, v19
	v_mul_f32_e32 v27, 0x4b800000, v19
	s_mov_b32 s4, 0x800000
	v_cmp_gt_f32_e32 vcc, s4, v19
	s_nop 1
	v_cndmask_b32_e32 v19, v19, v27, vcc
	v_rsq_f32_e32 v19, v19
	s_nop 0
	v_mul_f32_e32 v27, 0x45800000, v19
	v_cndmask_b32_e32 v32, v19, v27, vcc
	s_waitcnt vmcnt(0)
	v_pk_add_f32 v[72:73], v[72:73], v[36:37] op_sel_hi:[1,0] neg_lo:[0,1] neg_hi:[0,1]
	v_pk_add_f32 v[74:75], v[74:75], v[36:37] op_sel_hi:[1,0] neg_lo:[0,1] neg_hi:[0,1]
	v_pk_add_f32 v[76:77], v[76:77], v[36:37] op_sel_hi:[1,0] neg_lo:[0,1] neg_hi:[0,1]
	v_pk_add_f32 v[78:79], v[78:79], v[36:37] op_sel_hi:[1,0] neg_lo:[0,1] neg_hi:[0,1]
	v_pk_add_f32 v[80:81], v[80:81], v[36:37] op_sel_hi:[1,0] neg_lo:[0,1] neg_hi:[0,1]
	v_pk_add_f32 v[82:83], v[82:83], v[36:37] op_sel_hi:[1,0] neg_lo:[0,1] neg_hi:[0,1]
	v_pk_add_f32 v[84:85], v[84:85], v[36:37] op_sel_hi:[1,0] neg_lo:[0,1] neg_hi:[0,1]
	v_pk_add_f32 v[86:87], v[86:87], v[36:37] op_sel_hi:[1,0] neg_lo:[0,1] neg_hi:[0,1]
	v_pk_add_f32 v[120:121], v[120:121], 1.0 op_sel_hi:[1,0]
	v_pk_add_f32 v[122:123], v[122:123], 1.0 op_sel_hi:[1,0]
	v_pk_add_f32 v[124:125], v[124:125], 1.0 op_sel_hi:[1,0]
	v_pk_add_f32 v[126:127], v[126:127], 1.0 op_sel_hi:[1,0]
	v_pk_add_f32 v[128:129], v[128:129], 1.0 op_sel_hi:[1,0]
	v_pk_add_f32 v[130:131], v[130:131], 1.0 op_sel_hi:[1,0]
	v_pk_add_f32 v[132:133], v[132:133], 1.0 op_sel_hi:[1,0]
	v_pk_add_f32 v[134:135], v[134:135], 1.0 op_sel_hi:[1,0]
	v_pk_mul_f32 v[72:73], v[32:33], v[72:73] op_sel_hi:[0,1]
	v_pk_mul_f32 v[74:75], v[32:33], v[74:75] op_sel_hi:[0,1]
	v_pk_mul_f32 v[76:77], v[32:33], v[76:77] op_sel_hi:[0,1]
	v_pk_mul_f32 v[78:79], v[32:33], v[78:79] op_sel_hi:[0,1]
	v_pk_mul_f32 v[80:81], v[32:33], v[80:81] op_sel_hi:[0,1]
	v_pk_mul_f32 v[82:83], v[32:33], v[82:83] op_sel_hi:[0,1]
	v_pk_mul_f32 v[84:85], v[32:33], v[84:85] op_sel_hi:[0,1]
	v_pk_mul_f32 v[86:87], v[32:33], v[86:87] op_sel_hi:[0,1]
	v_pk_fma_f32 v[72:73], v[72:73], v[88:89], v[104:105]
	v_pk_fma_f32 v[74:75], v[74:75], v[90:91], v[106:107]
	v_pk_fma_f32 v[76:77], v[76:77], v[92:93], v[108:109]
	v_pk_fma_f32 v[78:79], v[78:79], v[94:95], v[110:111]
	v_pk_fma_f32 v[80:81], v[80:81], v[96:97], v[112:113]
	v_pk_fma_f32 v[82:83], v[82:83], v[98:99], v[114:115]
	v_pk_fma_f32 v[84:85], v[84:85], v[100:101], v[116:117]
	v_pk_fma_f32 v[86:87], v[86:87], v[102:103], v[118:119]
	v_pk_fma_f32 v[72:73], v[72:73], v[120:121], v[146:147]
	v_pk_fma_f32 v[74:75], v[74:75], v[122:123], v[148:149]
	v_pk_fma_f32 v[76:77], v[76:77], v[124:125], v[150:151]
	v_pk_fma_f32 v[78:79], v[78:79], v[126:127], v[152:153]
	v_pk_fma_f32 v[80:81], v[80:81], v[128:129], v[154:155]
	v_pk_fma_f32 v[82:83], v[82:83], v[130:131], v[156:157]
	v_pk_fma_f32 v[84:85], v[84:85], v[132:133], v[158:159]
	v_pk_fma_f32 v[86:87], v[86:87], v[134:135], v[160:161]
	v_cvt_pk_bf16_f32 v72, v72, v73
	v_cvt_pk_bf16_f32 v73, v74, v75
	v_cvt_pk_bf16_f32 v76, v76, v77
	v_cvt_pk_bf16_f32 v77, v78, v79
	v_cvt_pk_bf16_f32 v80, v80, v81
	v_cvt_pk_bf16_f32 v81, v82, v83
	v_cvt_pk_bf16_f32 v84, v84, v85
	v_cvt_pk_bf16_f32 v85, v86, v87
	global_store_dwordx2 v[34:35], v[72:73], off
	global_store_dwordx2 v[34:35], v[76:77], off offset:512
	global_store_dwordx2 v[34:35], v[80:81], off offset:1024
	global_store_dwordx2 v[34:35], v[84:85], off offset:1536
	v_add_u32_e32 v16, 1, v16
	s_sub_i32 s6, s6, 1
	s_cmp_lg_u32 s6, 0
	s_cbranch_scc1 .LxnF2_loop
	s_branch .LBB0_978
